# v22: phase_norm reads its per-row modulation vectors from an LDS copy (staged once by LDS-DMA) so vmcnt waits no longer drain the next-row prefetch
# speedup vs baseline: 1.0054x; 1.0054x over previous
; __device__ void phase_norm(const float* xsrc, const float* csrc, const float* ng, const float* mod, bf16_t* H) {
;   const int lane = threadIdx.x & 63, gw = blockIdx.x * 8 + (threadIdx.x >> 6), nw = gridDim.x * 8;
;   f32x4 g4[4];
; #pragma unroll
;   for (int i = 0; i < 4; ++i) g4[i] = *(const f32x4*)(ng + i * 256 + lane * 4);
;   f32x4 va[4], vb[4]; int bia = 0, bib = 0;
;   if (gw < NTOK) { const float* src = row_src(xsrc, csrc, gw, bia);
; #pragma unroll
;     for (int i = 0; i < 4; ++i) va[i] = *(const f32x4*)(src + i * 256 + lane * 4); }
;   for (int n = gw; n < NTOK; n += nw) {
;     if (n + nw < NTOK) { const float* src = row_src(xsrc, csrc, n + nw, bib);
; #pragma unroll
;       for (int i = 0; i < 4; ++i) vb[i] = *(const f32x4*)(src + i * 256 + lane * 4); }
;     float ss = 0.f;
; #pragma unroll
;     for (int i = 0; i < 4; ++i) ss += va[i][0] * va[i][0] + va[i][1] * va[i][1] + va[i][2] * va[i][2] + va[i][3] * va[i][3];
;     ss = wave_sum(ss);
;     const float rstd = rsqrtf(ss * (1.f / 1024.f) + 1e-6f);
;     const float* m = mod + bia * 3072;
.LBB0_676:
	s_or_b64 exec, exec, s[8:9]
	v_and_b32_e32 v32, 0xfc, v186
	v_mov_b32_e32 v167, 0
	v_lshlrev_b32_e32 v166, 2, v32
	s_barrier
	s_and_saveexec_b64 s[8:9], s[4:5]
	s_cbranch_execz .LBB0_689
	v_lshl_add_u64 v[0:1], s[44:45], 0, v[166:167]
	s_mov_b64 s[0:1], 0x1000
	v_lshl_add_u64 v[16:17], v[0:1], 0, s[0:1]
	v_add_co_u32_e32 v18, vcc, 0x1000, v0
	s_mov_b32 s0, 0x3e0f83e1
	s_nop 0
	v_addc_co_u32_e32 v19, vcc, 0, v1, vcc
	global_load_dwordx4 v[0:3], v[16:17], off offset:1024
	global_load_dwordx4 v[4:7], v[16:17], off offset:2048
	global_load_dwordx4 v[8:11], v[18:19], off
	global_load_dwordx4 v[12:15], v[16:17], off offset:3072
	v_mul_hi_i32 v16, v176, s0
	v_lshrrev_b32_e32 v17, 31, v16
	v_ashrrev_i32_e32 v16, 11, v16
	v_add_u32_e32 v16, v16, v17
	s_movk_i32 s0, 0xdf00
	v_mad_i32_i24 v18, v16, s0, v176
	s_movk_i32 s0, 0x1fff
	v_cmp_lt_i32_e32 vcc, s0, v18
	v_mov_b64_e32 v[20:21], s[84:85]
	s_and_saveexec_b64 s[0:1], vcc
	s_xor_b64 s[4:5], exec, s[0:1]
	v_add_u32_e32 v18, 0xffffe000, v18
	v_mov_b32_e32 v19, 0
	v_mov_b64_e32 v[20:21], s[6:7]
	s_or_saveexec_b64 s[4:5], s[4:5]
	v_mov_b32_e32 v51, 8
	v_mov_b64_e32 v[22:23], 20
	s_xor_b64 exec, exec, s[4:5]
	v_ashrrev_i32_e32 v19, 31, v18
	v_mov_b64_e32 v[22:23], 25
	v_mov_b32_e32 v51, v16
	s_or_b64 exec, exec, s[4:5]
	v_ashrrev_i32_e32 v17, 31, v16
	v_lshlrev_b64 v[16:17], v22, v[16:17]
	v_lshl_add_u64 v[16:17], v[20:21], 0, v[16:17]
	v_lshlrev_b64 v[18:19], 12, v[18:19]
	v_lshl_add_u64 v[16:17], v[16:17], 0, v[18:19]
	v_mov_b32_e32 v167, 0
	v_lshl_add_u64 v[34:35], v[16:17], 0, v[166:167]
	global_load_dwordx4 v[16:19], v[34:35], off offset:3072
	global_load_dwordx4 v[20:23], v[34:35], off offset:2048
	global_load_dwordx4 v[24:27], v[34:35], off offset:1024
	global_load_dwordx4 v[28:31], v[34:35], off
	v_mbcnt_lo_u32_b32 v33, -1, 0
	v_mbcnt_hi_u32_b32 v33, -1, v33
	v_and_b32_e32 v34, 64, v33
	v_add_u32_e32 v34, 64, v34
	v_xor_b32_e32 v35, 32, v33
	v_cmp_lt_i32_e32 vcc, v35, v34
	v_lshlrev_b64 v[38:39], 11, v[176:177]
	s_add_u32 s10, s86, 0x3d77b000
	v_cndmask_b32_e32 v35, v33, v35, vcc
	v_lshlrev_b32_e32 v56, 2, v35
	v_xor_b32_e32 v35, 16, v33
	v_cmp_lt_i32_e32 vcc, v35, v34
	v_lshl_or_b32 v38, v160, 3, v38
	s_addc_u32 s11, s87, 0
	v_cndmask_b32_e32 v35, v33, v35, vcc
	v_lshlrev_b32_e32 v57, 2, v35
	v_xor_b32_e32 v35, 8, v33
	v_cmp_lt_i32_e32 vcc, v35, v34
	v_or_b32_e32 v36, 0x200, v32
	v_lshl_add_u64 v[38:39], s[86:87], 0, v[38:39]
	v_cndmask_b32_e32 v35, v33, v35, vcc
	s_waitcnt vmcnt(13)
	v_lshlrev_b32_e32 v58, 2, v35
	v_xor_b32_e32 v35, 4, v33
	v_cmp_lt_i32_e32 vcc, v35, v34
	s_mov_b64 s[0:1], 0x400
	s_ashr_i32 s43, s42, 31
	v_cndmask_b32_e32 v35, v33, v35, vcc
	v_lshlrev_b32_e32 v59, 2, v35
	v_xor_b32_e32 v35, 2, v33
	v_cmp_lt_i32_e32 vcc, v35, v34
	v_lshl_add_u64 v[48:49], v[38:39], 0, s[0:1]
	s_lshl_b64 s[12:13], s[42:43], 11
	v_cndmask_b32_e32 v35, v33, v35, vcc
	v_lshlrev_b32_e32 v60, 2, v35
	v_xor_b32_e32 v35, 1, v33
	v_cmp_lt_i32_e32 vcc, v35, v34
	v_or_b32_e32 v34, 0x100, v32
	v_or_b32_e32 v32, 0x300, v32
	v_cndmask_b32_e32 v33, v33, v35, vcc
	v_lshlrev_b32_e32 v61, 2, v33
	s_mov_b64 s[14:15], 0
	s_mov_b32 s0, 0x10800
	s_mov_b32 s1, 0x107ff
	s_mov_b32 s2, 0x3e0f83e1
	s_movk_i32 s20, 0x1fff
	s_waitcnt vmcnt(12)
	v_mov_b32_e32 v62, 0x358637bd
	s_mov_b32 s21, 0x800000
	s_movk_i32 s22, 0xc00
	s_mov_b64 s[16:17], 0x1000
	v_lshlrev_b32_e32 v50, 2, v34
	v_lshlrev_b32_e32 v52, 2, v36
	v_lshlrev_b32_e32 v54, 2, v32
	v_mov_b32_e32 v53, v176
	v_mov_b32_e32 v64, v167
	v_readfirstlane_b32 s60, v182
	s_nop 0
	s_lshl_b32 s60, s60, 10
	v_add_u32_e32 v101, s60, v166
	s_mov_b64 s[62:63], s[10:11]
	s_add_i32 m0, s60, 0x0
	s_nop 0
	global_load_lds_dwordx4 v101, s[62:63]
	s_add_u32 s62, s62, 0x3000
	s_addc_u32 s63, s63, 0
	s_add_i32 m0, s60, 0x2000
	s_nop 0
	global_load_lds_dwordx4 v101, s[62:63]
	s_add_u32 s62, s62, 0x3000
	s_addc_u32 s63, s63, 0
	s_add_i32 m0, s60, 0x4000
	s_nop 0
	global_load_lds_dwordx4 v101, s[62:63]
	s_add_u32 s62, s62, 0x3000
	s_addc_u32 s63, s63, 0
	s_add_i32 m0, s60, 0x6000
	s_nop 0
	global_load_lds_dwordx4 v101, s[62:63]
	s_add_u32 s62, s62, 0x3000
	s_addc_u32 s63, s63, 0
	s_add_i32 m0, s60, 0x8000
	s_nop 0
	global_load_lds_dwordx4 v101, s[62:63]
	s_add_u32 s62, s62, 0x3000
	s_addc_u32 s63, s63, 0
	s_add_i32 m0, s60, 0xa000
	s_nop 0
	global_load_lds_dwordx4 v101, s[62:63]
	s_add_u32 s62, s62, 0x3000
	s_addc_u32 s63, s63, 0
	s_add_i32 m0, s60, 0xc000
	s_nop 0
	global_load_lds_dwordx4 v101, s[62:63]
	s_add_u32 s62, s62, 0x3000
	s_addc_u32 s63, s63, 0
	s_add_i32 m0, s60, 0xe000
	s_nop 0
	global_load_lds_dwordx4 v101, s[62:63]
	s_add_u32 s62, s62, 0x3000
	s_addc_u32 s63, s63, 0
	s_add_i32 m0, s60, 0x10000
	s_nop 0
	global_load_lds_dwordx4 v101, s[62:63]
	s_add_u32 s62, s62, 0x3000
	s_addc_u32 s63, s63, 0
	s_waitcnt vmcnt(0)
	s_barrier
	s_mov_b32 m0, -1
	s_branch .LBB0_684

; __device__ __forceinline__ void st_bf16x4(bf16_t* p, float a, float b, float c, float d) { u32x2 w = {cvtpk(a, b), cvtpk(c, d)}; *(u32x2*)p = w; }
; __device__ void phase_norm(const float* xsrc, const float* csrc, const float* ng, const float* mod, bf16_t* H) {
;     ...
;   for (int n = gw; n < NTOK; n += nw) {
;     if (n + nw < NTOK) { const float* src = row_src(xsrc, csrc, n + nw, bib);
; #pragma unroll
;       for (int i = 0; i < 4; ++i) vb[i] = *(const f32x4*)(src + i * 256 + lane * 4); }
;     float ss = 0.f;
; #pragma unroll
;     for (int i = 0; i < 4; ++i) ss += va[i][0] * va[i][0] + va[i][1] * va[i][1] + va[i][2] * va[i][2] + va[i][3] * va[i][3];
;     ss = wave_sum(ss);
;     const float rstd = rsqrtf(ss * (1.f / 1024.f) + 1e-6f);
;     const float* m = mod + bia * 3072;
; #pragma unroll
;     for (int i = 0; i < 4; ++i) {
;       const int c = i * 256 + lane * 4;
;       const f32x4 sh = *(const f32x4*)(m + c), sc = *(const f32x4*)(m + 1024 + c);
;       float o[4];
; #pragma unroll
;       for (int e = 0; e < 4; ++e) o[e] = va[i][e] * rstd * g4[i][e] * (1.f + sc[e]) + sh[e];
;       st_bf16x4(H + (size_t)n * 1024 + c, o[0], o[1], o[2], o[3]);
;     }
; #pragma unroll
;     for (int i = 0; i < 4; ++i) va[i] = vb[i];
;     bia = bib;
;   }
.LBB0_683:
	s_or_b64 exec, exec, s[18:19]
	v_mul_lo_u32 v66, v51, s22
	v_lshl_add_u32 v100, v51, 13, v166
	v_ashrrev_i32_e32 v67, 31, v66
	v_lshl_add_u64 v[70:71], v[66:67], 2, s[10:11]
	v_lshl_add_u64 v[74:75], v[70:71], 0, s[16:17]
	v_lshl_add_u64 v[66:67], v[74:75], 0, v[166:167]
	ds_read_b128 v[66:69], v100 offset:4096
	v_lshl_add_u64 v[76:77], v[70:71], 0, v[166:167]
	ds_read_b128 v[70:73], v100
	s_waitcnt vmcnt(4)
	s_nop 0
	s_nop 0
	s_nop 0
	s_nop 0
	s_nop 0
	s_nop 0
	v_mul_f32_e64 v80, v25, v25
	v_mul_f32_e64 v81, v29, v29
	v_mov_b32_e32 v82, v26
	v_mov_b32_e32 v83, v30
	v_mov_b32_e32 v86, v16
	v_mov_b32_e32 v87, v20
	v_mul_f32_e64 v88, v17, v17
	v_mul_f32_e64 v89, v21, v21
	v_fma_f32 v78, v24, v24, v80
	v_fma_f32 v79, v28, v28, v81
	v_mov_b32_e32 v84, v27
	v_mov_b32_e32 v85, v31
	v_mov_b32_e32 v90, v18
	v_mov_b32_e32 v91, v22
	v_fma_f32 v80, v86, v86, v88
	v_fma_f32 v81, v87, v87, v89
	v_fma_f32 v78, v82, v82, v78
	v_fma_f32 v79, v83, v83, v79
	v_mov_b32_e32 v92, v19
	v_mov_b32_e32 v93, v23
	v_fma_f32 v80, v90, v90, v80
	v_fma_f32 v81, v91, v91, v81
	v_fma_f32 v78, v84, v84, v78
	v_fma_f32 v79, v85, v85, v79
	v_fma_f32 v80, v92, v92, v80
	v_fma_f32 v81, v93, v93, v81
	v_add_f32_e32 v51, v78, v79
	v_add_f32_e32 v51, v81, v51
	v_add_f32_e32 v51, v80, v51
	ds_bpermute_b32 v53, v56, v51
	s_and_b64 s[4:5], exec, vcc
	v_mov_b32_e32 v55, v167
	s_or_b64 s[14:15], s[4:5], s[14:15]
	s_waitcnt lgkmcnt(0)
	v_add_f32_e32 v51, v51, v53
	ds_bpermute_b32 v53, v57, v51
	s_waitcnt lgkmcnt(0)
	v_add_f32_e32 v51, v51, v53
	ds_bpermute_b32 v53, v58, v51
	s_waitcnt lgkmcnt(0)
	v_add_f32_e32 v51, v51, v53
	ds_bpermute_b32 v53, v59, v51
	s_waitcnt lgkmcnt(0)
	v_add_f32_e32 v51, v51, v53
	ds_bpermute_b32 v53, v60, v51
	s_waitcnt lgkmcnt(0)
	v_add_f32_e32 v51, v51, v53
	ds_bpermute_b32 v53, v61, v51
	s_waitcnt lgkmcnt(0)
	v_add_f32_e32 v51, v51, v53
	v_fmamk_f32 v51, v51, 0x3a800000, v62
	v_mul_f32_e32 v53, 0x4b800000, v51
	v_cmp_gt_f32_e32 vcc, s21, v51
	s_waitcnt lgkmcnt(1)
	v_add_f32_e64 v66, v66, 1.0
	v_add_f32_e64 v67, v67, 1.0
	v_cndmask_b32_e32 v51, v51, v53, vcc
	v_rsq_f32_e32 v53, v51
	v_mov_b32_e32 v51, v167
	v_lshl_add_u64 v[78:79], v[74:75], 0, v[50:51]
	v_add_f32_e64 v68, v68, 1.0
	v_add_f32_e64 v69, v69, 1.0
	v_mul_f32_e32 v51, 0x45800000, v53
	v_cndmask_b32_e32 v80, v53, v51, vcc
	v_mul_f32_e64 v28, v28, v80
	v_mul_f32_e64 v29, v29, v80
	v_mul_f32_e64 v30, v30, v80
	v_mul_f32_e64 v31, v31, v80
	v_mul_f32_e64 v28, v8, v28
	v_mul_f32_e64 v29, v9, v29
	v_mul_f32_e64 v30, v10, v30
	v_mul_f32_e64 v31, v11, v31
	s_waitcnt lgkmcnt(0)
	v_fma_f32 v28, v66, v28, v70
	v_fma_f32 v29, v67, v29, v71
	v_fma_f32 v30, v68, v30, v72
	v_fma_f32 v31, v69, v31, v73
	v_cvt_pk_bf16_f32 v28, v28, v29
	v_cvt_pk_bf16_f32 v29, v30, v31
	global_store_dwordx2 v[48:49], v[28:29], off offset:-1024
	ds_read_b128 v[28:31], v100 offset:5120
	s_nop 0
	ds_read_b128 v[66:69], v100 offset:1024
	v_mul_f32_e64 v24, v24, v80
	v_mul_f32_e64 v25, v25, v80
	v_mul_f32_e64 v26, v26, v80
	v_mul_f32_e64 v27, v27, v80
	v_mul_f32_e64 v24, v0, v24
	v_mul_f32_e64 v25, v1, v25
	v_mul_f32_e64 v26, v2, v26
	v_mul_f32_e64 v27, v3, v27
	v_mov_b32_e32 v53, v167
	v_lshl_add_u64 v[70:71], v[74:75], 0, v[52:53]
	v_mul_f32_e64 v20, v20, v80
	v_mul_f32_e64 v21, v21, v80
	v_mul_f32_e64 v22, v22, v80
	v_mul_f32_e64 v23, v23, v80
	v_mul_f32_e64 v20, v4, v20
	v_mul_f32_e64 v21, v5, v21
	v_mul_f32_e64 v22, v6, v22
	v_mul_f32_e64 v23, v7, v23
	v_lshl_add_u64 v[74:75], v[74:75], 0, v[54:55]
	v_mov_b32_e32 v53, v63
	v_mov_b32_e32 v51, v64
	s_waitcnt lgkmcnt(1)
	v_add_f32_e64 v28, v28, 1.0
	v_add_f32_e64 v29, v29, 1.0
	v_add_f32_e64 v30, v30, 1.0
	v_add_f32_e64 v31, v31, 1.0
	s_waitcnt lgkmcnt(0)
	v_fma_f32 v24, v28, v24, v66
	v_fma_f32 v25, v29, v25, v67
	v_fma_f32 v26, v30, v26, v68
	v_fma_f32 v27, v31, v27, v69
	v_cvt_pk_bf16_f32 v24, v24, v25
	v_cvt_pk_bf16_f32 v25, v26, v27
	global_store_dwordx2 v[48:49], v[24:25], off offset:-512
	ds_read_b128 v[24:27], v100 offset:6144
	s_nop 0
	ds_read_b128 v[28:31], v100 offset:2048
	s_waitcnt lgkmcnt(1)
	v_add_f32_e64 v24, v24, 1.0
	v_add_f32_e64 v25, v25, 1.0
	v_add_f32_e64 v26, v26, 1.0
	v_add_f32_e64 v27, v27, 1.0
	s_waitcnt lgkmcnt(0)
	v_fma_f32 v20, v24, v20, v28
	v_fma_f32 v21, v25, v21, v29
	v_fma_f32 v22, v26, v22, v30
	v_fma_f32 v23, v27, v23, v31
	v_cvt_pk_bf16_f32 v20, v20, v21
	v_cvt_pk_bf16_f32 v21, v22, v23
	global_store_dwordx2 v[48:49], v[20:21], off
	ds_read_b128 v[66:69], v100 offset:7168
	ds_read_b128 v[70:73], v100 offset:3072
	v_mul_f32_e64 v74, v16, v80
	v_mul_f32_e64 v75, v17, v80
	v_mul_f32_e64 v76, v18, v80
	v_mul_f32_e64 v77, v19, v80
	v_mul_f32_e64 v74, v12, v74
	v_mul_f32_e64 v75, v13, v75
	v_mul_f32_e64 v76, v14, v76
	v_mul_f32_e64 v77, v15, v77
	s_waitcnt vmcnt(3)
	v_mov_b64_e32 v[16:17], v[44:45]
	v_mov_b64_e32 v[20:21], v[40:41]
	v_mov_b64_e32 v[24:25], v[36:37]
	v_mov_b64_e32 v[28:29], v[32:33]
	v_mov_b64_e32 v[18:19], v[46:47]
	v_mov_b64_e32 v[22:23], v[42:43]
	v_mov_b64_e32 v[26:27], v[38:39]
	v_mov_b64_e32 v[30:31], v[34:35]
	s_waitcnt lgkmcnt(1)
	v_add_f32_e64 v66, v66, 1.0
	v_add_f32_e64 v67, v67, 1.0
	v_add_f32_e64 v68, v68, 1.0
	v_add_f32_e64 v69, v69, 1.0
	s_waitcnt lgkmcnt(0)
	v_fma_f32 v66, v74, v66, v70
	v_fma_f32 v67, v75, v67, v71
	v_fma_f32 v68, v76, v68, v72
	v_fma_f32 v69, v77, v69, v73
	v_cvt_pk_bf16_f32 v66, v66, v67
	v_cvt_pk_bf16_f32 v67, v68, v69
	global_store_dwordx2 v[48:49], v[66:67], off offset:512
	v_lshl_add_u64 v[48:49], v[48:49], 0, s[12:13]
	s_andn2_b64 exec, exec, s[14:15]
	s_cbranch_execz .LBB0_689
